# resid+norm epilogue second pass: gain/scale/shift of column groups 1-3 prefetched with group 0 (one L2 round trip), per-group loads become register copies
# speedup vs baseline: 1.0701x; 1.0006x over previous
;     __device__ __forceinline__ void fused(f32x4 (&acc)[2][2][4][2], const Unit& u, int wr, int wc, int fr, int fq, ldsp lds, int wid, int lane) const {
;     ...
;         const int colt = u.pn * BM + wc * 32 + 4 * fq;
;         const float* mb = modn + (size_t)b * NMOD;
; #pragma unroll
;         for (int bj = 0; bj < 2; ++bj)
; #pragma unroll
;             for (int n = 0; n < 2; ++n) { const int c = colt + bj * HALF + n * 16;
;                 f32x4 gc = *(const f32x4*)(gain + c), sh = (f32x4){0.f, 0.f, 0.f, 0.f};
;                 if (!fin) { gc = gc * (*(const f32x4*)(mb + scoff + c) + 1.0f); sh = *(const f32x4*)(mb + shoff + c); }
.LBB0_449:
	s_or_b64 exec, exec, s[22:23]
	v_or_b32_e32 v142, s14, v149
	v_ashrrev_i32_e32 v143, 31, v142
	s_waitcnt vmcnt(0) lgkmcnt(0)
	s_barrier
	v_lshl_add_u64 v[144:145], v[142:143], 2, s[6:7]
	global_load_dwordx4 v[102:105], v[144:145], off
	global_load_dwordx4 v[162:165], v[144:145], off offset:64
	global_load_dwordx4 v[166:169], v[144:145], off offset:512
	global_load_dwordx4 v[170:173], v[144:145], off offset:576
	s_load_dwordx2 s[4:5], s[62:63], 0xc0
	s_lshl_b64 s[0:1], s[16:17], 2
	v_mov_b32_e32 v110, 0
	s_waitcnt lgkmcnt(0)
	s_add_u32 s0, s4, s0
	s_addc_u32 s1, s5, s1
	s_add_u32 s0, s0, s30
	s_addc_u32 s1, s1, s31
	s_and_b64 vcc, exec, s[10:11]
	s_cbranch_vccnz .LBB0_451
	s_lshl_b32 s3, s81, 2
	s_add_u32 s4, s0, s3
	s_addc_u32 s5, s1, 0
	v_lshlrev_b64 v[110:111], 2, v[142:143]
	s_lshl_b32 s3, s88, 2
	v_lshl_add_u64 v[118:119], s[4:5], 0, v[110:111]
	s_add_u32 s4, s0, s3
	s_addc_u32 s5, s1, 0
	v_lshl_add_u64 v[110:111], s[4:5], 0, v[110:111]
	global_load_dwordx4 v[174:177], v[110:111], off offset:64
	global_load_dwordx4 v[178:181], v[110:111], off offset:512
	global_load_dwordx4 v[182:185], v[110:111], off offset:576
	global_load_dwordx4 v[226:229], v[118:119], off offset:64
	global_load_dwordx4 v[230:233], v[118:119], off offset:512
	global_load_dwordx4 v[234:237], v[118:119], off offset:576
	global_load_dwordx4 v[110:113], v[110:111], off
	s_waitcnt vmcnt(0)
	v_pk_add_f32 v[112:113], v[112:113], 1.0 op_sel_hi:[1,0]
	v_pk_add_f32 v[110:111], v[110:111], 1.0 op_sel_hi:[1,0]
	v_pk_mul_f32 v[104:105], v[104:105], v[112:113]
	v_pk_mul_f32 v[102:103], v[102:103], v[110:111]
	global_load_dwordx4 v[110:113], v[118:119], off
	s_branch .LBB0_452

;     __device__ __forceinline__ void fused(f32x4 (&acc)[2][2][4][2], const Unit& u, int wr, int wc, int fr, int fq, ldsp lds, int wid, int lane) const {
;     ...
;             for (int n = 0; n < 2; ++n) { const int c = colt + bj * HALF + n * 16;
;                 f32x4 gc = *(const f32x4*)(gain + c), sh = (f32x4){0.f, 0.f, 0.f, 0.f};
;                 if (!fin) { gc = gc * (*(const f32x4*)(mb + scoff + c) + 1.0f); sh = *(const f32x4*)(mb + shoff + c); }
.LBB0_482:
	s_nop 1
	v_mov_b64_e32 v[98:99], v[162:163]
	v_mov_b64_e32 v[100:101], v[164:165]
	s_and_b64 vcc, exec, s[10:11]
	v_mov_b32_e32 v102, 0
	s_cbranch_vccnz .LBB0_486
.LBB0_483:
	s_lshl_b32 s3, s81, 2
	s_add_u32 s4, s0, s3
	s_addc_u32 s5, s1, 0
	v_lshlrev_b64 v[102:103], 2, v[142:143]
	s_lshl_b32 s3, s88, 2
	v_lshl_add_u64 v[108:109], s[4:5], 0, v[102:103]
	s_add_u32 s4, s0, s3
	s_addc_u32 s5, s1, 0
	v_lshl_add_u64 v[102:103], s[4:5], 0, v[102:103]
	v_mov_b64_e32 v[102:103], v[174:175]
	v_mov_b64_e32 v[104:105], v[176:177]
	v_pk_add_f32 v[104:105], v[104:105], 1.0 op_sel_hi:[1,0]
	v_pk_add_f32 v[102:103], v[102:103], 1.0 op_sel_hi:[1,0]
	v_pk_mul_f32 v[100:101], v[100:101], v[104:105]
	v_pk_mul_f32 v[98:99], v[98:99], v[102:103]
	v_mov_b64_e32 v[102:103], v[226:227]
	v_mov_b64_e32 v[104:105], v[228:229]
	s_branch .LBB0_487

;     __device__ __forceinline__ void fused(f32x4 (&acc)[2][2][4][2], const Unit& u, int wr, int wc, int fr, int fq, ldsp lds, int wid, int lane) const {
;     ...
;             for (int n = 0; n < 2; ++n) { const int c = colt + bj * HALF + n * 16;
;                 f32x4 gc = *(const f32x4*)(gain + c), sh = (f32x4){0.f, 0.f, 0.f, 0.f};
;                 if (!fin) { gc = gc * (*(const f32x4*)(mb + scoff + c) + 1.0f); sh = *(const f32x4*)(mb + shoff + c); }
; #pragma unroll
;                 for (int ai = 0; ai < 2; ++ai)
; #pragma unroll
;                     for (int m = 0; m < 4; ++m) { const int r = ai * HALF + wr * 64 + m * 16 + fr; const float rs = Sx[r];
;                         const f32x4 y = (acc[ai][bj][m][n] * rs) * gc + sh;
;                         if (fin) *(f32x4*)(xd + (size_t)(rowt + r) * D + c) = y;
.LBB0_485:
	v_add_u32_e32 v102, s8, v106
	v_ashrrev_i32_e32 v103, 31, v102
	v_lshlrev_b64 v[102:103], 12, v[102:103]
	v_lshl_add_u64 v[102:103], s[54:55], 0, v[102:103]
	v_lshl_add_u64 v[102:103], v[142:143], 2, v[102:103]
	global_store_dwordx4 v[102:103], v[98:101], off
	s_nop 1
	v_mov_b64_e32 v[98:99], v[162:163]
	v_mov_b64_e32 v[100:101], v[164:165]
	s_and_b64 vcc, exec, s[10:11]
	v_mov_b32_e32 v102, 0
	s_cbranch_vccz .LBB0_483

; __device__ __forceinline__ unsigned cvt_pk_bf16(float lo, float hi) { unsigned r; asm volatile("v_cvt_pk_bf16_f32 %0, %1, %2" : "=v"(r) : "v"(lo), "v"(hi)); return r; }
;     __device__ __forceinline__ void fused(f32x4 (&acc)[2][2][4][2], const Unit& u, int wr, int wc, int fr, int fq, ldsp lds, int wid, int lane) const {
;     ...
;                     for (int m = 0; m < 4; ++m) { const int r = ai * HALF + wr * 64 + m * 16 + fr; const float rs = Sx[r];
;                         const f32x4 y = (acc[ai][bj][m][n] * rs) * gc + sh;
;                         if (fin) *(f32x4*)(xd + (size_t)(rowt + r) * D + c) = y;
;                         else { u32x2 w; w.x = cvt_pk_bf16(y[0], y[1]); w.y = cvt_pk_bf16(y[2], y[3]); *(u32x2*)(H + (size_t)(rowt + r) * D + c) = w; } } }
.LBB0_487:
	ds_read_b32 v108, v96 offset:4096
	s_mov_b64 s[6:7], -1
	s_and_b64 vcc, exec, s[84:85]
	s_waitcnt lgkmcnt(0)
	v_pk_mul_f32 v[94:95], v[94:95], v[108:109] op_sel_hi:[1,0]
	v_pk_mul_f32 v[92:93], v[92:93], v[108:109] op_sel_hi:[1,0]
	v_pk_fma_f32 v[94:95], v[100:101], v[94:95], v[104:105]
	v_pk_fma_f32 v[92:93], v[98:99], v[92:93], v[102:103]
	s_cbranch_vccz .LBB0_489
	v_add_u32_e32 v110, s8, v148
	v_ashrrev_i32_e32 v111, 31, v110
	v_readlane_b32 s4, v254, 35
	v_lshlrev_b64 v[110:111], 11, v[110:111]
	v_readlane_b32 s5, v254, 36
	v_cvt_pk_bf16_f32 v108, v92, v93
	v_cvt_pk_bf16_f32 v109, v94, v95
	s_mov_b64 s[6:7], 0
	s_nop 0
	v_lshl_add_u64 v[110:111], s[4:5], 0, v[110:111]
	v_lshl_add_u64 v[110:111], v[142:143], 1, v[110:111]
	global_store_dwordx2 v[110:111], v[108:109], off offset:32

;     __device__ __forceinline__ void fused(f32x4 (&acc)[2][2][4][2], const Unit& u, int wr, int wc, int fr, int fq, ldsp lds, int wid, int lane) const {
;     ...
;             for (int n = 0; n < 2; ++n) { const int c = colt + bj * HALF + n * 16;
;                 f32x4 gc = *(const f32x4*)(gain + c), sh = (f32x4){0.f, 0.f, 0.f, 0.f};
;                 if (!fin) { gc = gc * (*(const f32x4*)(mb + scoff + c) + 1.0f); sh = *(const f32x4*)(mb + shoff + c); }
.LBB0_517:
	s_nop 1
	v_mov_b64_e32 v[64:65], v[166:167]
	v_mov_b64_e32 v[66:67], v[168:169]
	s_and_b64 vcc, exec, s[10:11]
	v_mov_b32_e32 v68, 0
	s_cbranch_vccnz .LBB0_521
.LBB0_518:
	s_lshl_b32 s3, s81, 2
	s_add_u32 s4, s0, s3
	s_addc_u32 s5, s1, 0
	v_lshlrev_b64 v[68:69], 2, v[142:143]
	s_lshl_b32 s3, s88, 2
	v_lshl_add_u64 v[72:73], s[4:5], 0, v[68:69]
	s_add_u32 s4, s0, s3
	s_addc_u32 s5, s1, 0
	v_lshl_add_u64 v[68:69], s[4:5], 0, v[68:69]
	v_mov_b64_e32 v[68:69], v[178:179]
	v_mov_b64_e32 v[70:71], v[180:181]
	v_pk_add_f32 v[70:71], v[70:71], 1.0 op_sel_hi:[1,0]
	v_pk_add_f32 v[68:69], v[68:69], 1.0 op_sel_hi:[1,0]
	v_pk_mul_f32 v[66:67], v[66:67], v[70:71]
	v_pk_mul_f32 v[64:65], v[64:65], v[68:69]
	v_mov_b64_e32 v[68:69], v[230:231]
	v_mov_b64_e32 v[70:71], v[232:233]
	s_branch .LBB0_522

;     __device__ __forceinline__ void fused(f32x4 (&acc)[2][2][4][2], const Unit& u, int wr, int wc, int fr, int fq, ldsp lds, int wid, int lane) const {
;     ...
;             for (int n = 0; n < 2; ++n) { const int c = colt + bj * HALF + n * 16;
;                 f32x4 gc = *(const f32x4*)(gain + c), sh = (f32x4){0.f, 0.f, 0.f, 0.f};
;                 if (!fin) { gc = gc * (*(const f32x4*)(mb + scoff + c) + 1.0f); sh = *(const f32x4*)(mb + shoff + c); }
; #pragma unroll
;                 for (int ai = 0; ai < 2; ++ai)
; #pragma unroll
;                     for (int m = 0; m < 4; ++m) { const int r = ai * HALF + wr * 64 + m * 16 + fr; const float rs = Sx[r];
;                         const f32x4 y = (acc[ai][bj][m][n] * rs) * gc + sh;
;                         if (fin) *(f32x4*)(xd + (size_t)(rowt + r) * D + c) = y;
.LBB0_520:
	v_add_u32_e32 v68, s8, v106
	v_ashrrev_i32_e32 v69, 31, v68
	v_lshlrev_b64 v[68:69], 12, v[68:69]
	v_lshl_add_u64 v[68:69], s[54:55], 0, v[68:69]
	v_lshl_add_u64 v[68:69], v[142:143], 2, v[68:69]
	global_store_dwordx4 v[68:69], v[64:67], off offset:64
	s_nop 1
	v_mov_b64_e32 v[64:65], v[166:167]
	v_mov_b64_e32 v[66:67], v[168:169]
	s_and_b64 vcc, exec, s[10:11]
	v_mov_b32_e32 v68, 0
	s_cbranch_vccz .LBB0_518

; __device__ __forceinline__ unsigned cvt_pk_bf16(float lo, float hi) { unsigned r; asm volatile("v_cvt_pk_bf16_f32 %0, %1, %2" : "=v"(r) : "v"(lo), "v"(hi)); return r; }
;     __device__ __forceinline__ void fused(f32x4 (&acc)[2][2][4][2], const Unit& u, int wr, int wc, int fr, int fq, ldsp lds, int wid, int lane) const {
;     ...
;                     for (int m = 0; m < 4; ++m) { const int r = ai * HALF + wr * 64 + m * 16 + fr; const float rs = Sx[r];
;                         const f32x4 y = (acc[ai][bj][m][n] * rs) * gc + sh;
;                         if (fin) *(f32x4*)(xd + (size_t)(rowt + r) * D + c) = y;
;                         else { u32x2 w; w.x = cvt_pk_bf16(y[0], y[1]); w.y = cvt_pk_bf16(y[2], y[3]); *(u32x2*)(H + (size_t)(rowt + r) * D + c) = w; } } }
.LBB0_522:
	ds_read_b32 v72, v96 offset:4096
	s_mov_b64 s[6:7], -1
	s_and_b64 vcc, exec, s[84:85]
	s_waitcnt lgkmcnt(0)
	v_pk_mul_f32 v[62:63], v[62:63], v[72:73] op_sel_hi:[1,0]
	v_pk_mul_f32 v[60:61], v[60:61], v[72:73] op_sel_hi:[1,0]
	v_pk_fma_f32 v[62:63], v[66:67], v[62:63], v[70:71]
	v_pk_fma_f32 v[60:61], v[64:65], v[60:61], v[68:69]
	s_cbranch_vccz .LBB0_524
	v_add_u32_e32 v74, s8, v148
	v_ashrrev_i32_e32 v75, 31, v74
	v_readlane_b32 s4, v254, 35
	v_lshlrev_b64 v[74:75], 11, v[74:75]
	v_readlane_b32 s5, v254, 36
	v_cvt_pk_bf16_f32 v72, v60, v61
	v_cvt_pk_bf16_f32 v73, v62, v63
	s_mov_b64 s[6:7], 0
	s_nop 0
	v_lshl_add_u64 v[74:75], s[4:5], 0, v[74:75]
	v_lshl_add_u64 v[74:75], v[142:143], 1, v[74:75]
	global_store_dwordx2 v[74:75], v[72:73], off offset:256

;     __device__ __forceinline__ void fused(f32x4 (&acc)[2][2][4][2], const Unit& u, int wr, int wc, int fr, int fq, ldsp lds, int wid, int lane) const {
;     ...
;             for (int n = 0; n < 2; ++n) { const int c = colt + bj * HALF + n * 16;
;                 f32x4 gc = *(const f32x4*)(gain + c), sh = (f32x4){0.f, 0.f, 0.f, 0.f};
;                 if (!fin) { gc = gc * (*(const f32x4*)(mb + scoff + c) + 1.0f); sh = *(const f32x4*)(mb + shoff + c); }
.LBB0_552:
	s_nop 1
	v_mov_b64_e32 v[32:33], v[170:171]
	v_mov_b64_e32 v[34:35], v[172:173]
	s_and_b64 vcc, exec, s[10:11]
	v_mov_b32_e32 v36, 0
	s_cbranch_vccnz .LBB0_556
.LBB0_553:
	s_lshl_b32 s3, s81, 2
	s_add_u32 s4, s0, s3
	s_addc_u32 s5, s1, 0
	s_lshl_b32 s3, s88, 2
	s_add_u32 s0, s0, s3
	v_lshlrev_b64 v[36:37], 2, v[142:143]
	s_addc_u32 s1, s1, 0
	v_lshl_add_u64 v[40:41], s[4:5], 0, v[36:37]
	v_lshl_add_u64 v[36:37], s[0:1], 0, v[36:37]
	v_mov_b64_e32 v[36:37], v[182:183]
	v_mov_b64_e32 v[38:39], v[184:185]
	v_pk_add_f32 v[38:39], v[38:39], 1.0 op_sel_hi:[1,0]
	v_pk_add_f32 v[36:37], v[36:37], 1.0 op_sel_hi:[1,0]
	v_pk_mul_f32 v[34:35], v[34:35], v[38:39]
	v_pk_mul_f32 v[32:33], v[32:33], v[36:37]
	v_mov_b64_e32 v[36:37], v[234:235]
	v_mov_b64_e32 v[38:39], v[236:237]
	s_branch .LBB0_557

;     __device__ __forceinline__ void fused(f32x4 (&acc)[2][2][4][2], const Unit& u, int wr, int wc, int fr, int fq, ldsp lds, int wid, int lane) const {
;     ...
;             for (int n = 0; n < 2; ++n) { const int c = colt + bj * HALF + n * 16;
;                 f32x4 gc = *(const f32x4*)(gain + c), sh = (f32x4){0.f, 0.f, 0.f, 0.f};
;                 if (!fin) { gc = gc * (*(const f32x4*)(mb + scoff + c) + 1.0f); sh = *(const f32x4*)(mb + shoff + c); }
; #pragma unroll
;                 for (int ai = 0; ai < 2; ++ai)
; #pragma unroll
;                     for (int m = 0; m < 4; ++m) { const int r = ai * HALF + wr * 64 + m * 16 + fr; const float rs = Sx[r];
;                         const f32x4 y = (acc[ai][bj][m][n] * rs) * gc + sh;
;                         if (fin) *(f32x4*)(xd + (size_t)(rowt + r) * D + c) = y;
.LBB0_555:
	v_add_u32_e32 v36, s8, v106
	v_ashrrev_i32_e32 v37, 31, v36
	v_lshlrev_b64 v[36:37], 12, v[36:37]
	v_lshl_add_u64 v[36:37], s[54:55], 0, v[36:37]
	v_lshl_add_u64 v[36:37], v[142:143], 2, v[36:37]
	global_store_dwordx4 v[36:37], v[32:35], off offset:512
	s_nop 1
	v_mov_b64_e32 v[32:33], v[170:171]
	v_mov_b64_e32 v[34:35], v[172:173]
	s_and_b64 vcc, exec, s[10:11]
	v_mov_b32_e32 v36, 0
	s_cbranch_vccz .LBB0_553

; __device__ __forceinline__ unsigned cvt_pk_bf16(float lo, float hi) { unsigned r; asm volatile("v_cvt_pk_bf16_f32 %0, %1, %2" : "=v"(r) : "v"(lo), "v"(hi)); return r; }
;     __device__ __forceinline__ void fused(f32x4 (&acc)[2][2][4][2], const Unit& u, int wr, int wc, int fr, int fq, ldsp lds, int wid, int lane) const {
;     ...
;                     for (int m = 0; m < 4; ++m) { const int r = ai * HALF + wr * 64 + m * 16 + fr; const float rs = Sx[r];
;                         const f32x4 y = (acc[ai][bj][m][n] * rs) * gc + sh;
;                         if (fin) *(f32x4*)(xd + (size_t)(rowt + r) * D + c) = y;
;                         else { u32x2 w; w.x = cvt_pk_bf16(y[0], y[1]); w.y = cvt_pk_bf16(y[2], y[3]); *(u32x2*)(H + (size_t)(rowt + r) * D + c) = w; } } }
.LBB0_557:
	ds_read_b32 v40, v96 offset:4096
	s_mov_b64 s[6:7], -1
	s_and_b64 vcc, exec, s[84:85]
	s_waitcnt lgkmcnt(0)
	v_pk_mul_f32 v[30:31], v[30:31], v[40:41] op_sel_hi:[1,0]
	v_pk_mul_f32 v[28:29], v[28:29], v[40:41] op_sel_hi:[1,0]
	v_pk_fma_f32 v[30:31], v[34:35], v[30:31], v[38:39]
	v_pk_fma_f32 v[28:29], v[32:33], v[28:29], v[36:37]
	s_cbranch_vccz .LBB0_559
	v_add_u32_e32 v42, s8, v148
	v_ashrrev_i32_e32 v43, 31, v42
	v_readlane_b32 s0, v254, 35
	v_lshlrev_b64 v[42:43], 11, v[42:43]
	v_readlane_b32 s1, v254, 36
	v_cvt_pk_bf16_f32 v40, v28, v29
	v_cvt_pk_bf16_f32 v41, v30, v31
	s_mov_b64 s[6:7], 0
	s_nop 0
	v_lshl_add_u64 v[42:43], s[0:1], 0, v[42:43]
	v_lshl_add_u64 v[42:43], v[142:143], 1, v[42:43]
	global_store_dwordx2 v[42:43], v[40:41], off offset:288
